# stack5: stack2 + ev lane^32 butterfly step via v_permlane32_swap + add (was 8 bpermute + 16 cndmask per token)
# speedup vs baseline: 1.0109x; 1.0109x over previous
; #define EV_IDS(t, i0, i1, c0, c1) do { i0 = sel_i[(size_t)(t) * 128 + lane]; i1 = sel_i[(size_t)(t) * 128 + 64 + lane]; \
;                                        c0 = cbuf[(size_t)(t) * 128 + lane]; c1 = cbuf[(size_t)(t) * 128 + 64 + lane]; } while (0)
; DI void ev_load(const unsigned char* __restrict__ vb8, const int id0, const int id1, const int cs, const int lane, uint4 (&v)[16]) {
; #pragma unroll
;   for (int i = 0; i < 16; ++i) {
;     const int id = __shfl(i < 8 ? id0 : id1, (8 * i + (lane >> 3)) & 63, 64);
;     v[i] = *(const uint4*)(vb8 + (size_t)id * 1024 + 128 * cs + 16 * (lane & 7));
;   }
; }
; DI void ev_compute(const uint4 (&v)[16], const float c0, const float c1, u16* __restrict__ yrow, const int lane) {
;   f32x2 acc[8];
; #pragma unroll
;   for (int k = 0; k < 8; ++k) acc[k] = f32x2{0.f, 0.f};
; #pragma unroll
;   for (int i = 0; i < 16; ++i) {
;     const float c = __shfl(i < 8 ? c0 : c1, (8 * i + (lane >> 3)) & 63, 64);
;     const f32x2 cc = f32x2{c, c};
;     f32x2 vf[8];
;     fp8x16_to_f32(v[i], vf);
; #pragma unroll
;     for (int k = 0; k < 8; ++k) acc[k] = __builtin_elementwise_fma(vf[k], cc, acc[k]);
;   }
; DI void phase_ev(const Params& p, const unsigned my_xcc, const unsigned my_rank) {
;     ...
;     for (int k = 0; k < K; k += 2) {
;       ev_load(vb8, b0, b1, cs, lane, vB);
;       const int tA2 = TOK(k + 2); int na0, na1; float nca0, nca1;
;       EV_IDS(tA2, na0, na1, nca0, nca1);
;       ev_compute(vA, ca0, ca1, ybuf + (size_t)tA * 1024 + 128 * cs, lane);
;       ev_load(vb8, na0, na1, cs, lane, vA);
;       const int tB2 = TOK(k + 3); int nb0, nb1; float ncb0, ncb1;
;       EV_IDS(tB2, nb0, nb1, ncb0, ncb1);
;       ev_compute(vB, cb0, cb1, ybuf + (size_t)tB * 1024 + 128 * cs, lane);
;       tA = tA2; a0 = na0; a1 = na1; ca0 = nca0; ca1 = nca1; tB = tB2; b0 = nb0; b1 = nb1; cb0 = ncb0; cb1 = ncb1;
.LBB0_570:
	s_add_i32 s24, s19, -1
	s_min_i32 s0, s24, s41
	s_waitcnt vmcnt(2)
	ds_bpermute_b32 v66, v168, v185
	s_mul_i32 s0, s0, s39
	s_add_i32 s0, s0, s33
	s_lshl_b32 s0, s0, 3
	s_add_i32 s20, s0, s38
	s_ashr_i32 s21, s20, 31
	s_waitcnt lgkmcnt(0)
	s_lshl_b64 s[0:1], s[20:21], 9
	v_or_b32_e32 v158, s0, v174
	v_mov_b32_e32 v159, s1
	v_lshl_add_u32 v66, v66, 10, v204
	v_lshl_add_u64 v[156:157], s[26:27], 0, v[158:159]
	global_load_dwordx4 v[126:129], v66, s[98:99]
	v_or_b32_e32 v160, 0x100, v158
	global_load_dword v157, v[156:157], off
	ds_bpermute_b32 v66, v169, v185
	v_lshl_add_u64 v[158:159], s[28:29], 0, v[158:159]
	global_load_dword v181, v[158:159], off
	v_mov_b32_e32 v161, s1
	v_lshl_add_u64 v[158:159], s[28:29], 0, v[160:161]
	s_waitcnt lgkmcnt(0)
	v_lshl_add_u32 v66, v66, 10, v204
	global_load_dwordx4 v[122:125], v66, s[98:99]
	ds_bpermute_b32 v66, v170, v185
	global_load_dword v182, v[158:159], off
	v_lshl_add_u64 v[162:163], s[26:27], 0, v[160:161]
	s_waitcnt vmcnt(5)
	ds_bpermute_b32 v158, v168, v155
	v_cvt_pk_f32_fp8_e32 v[160:161], v62
	s_waitcnt lgkmcnt(1)
	v_lshl_add_u32 v66, v66, 10, v204
	global_load_dwordx4 v[118:121], v66, s[98:99]
	ds_bpermute_b32 v66, v171, v185
	global_load_dword v156, v[162:163], off
	v_cvt_pk_f32_fp8_sdwa v[162:163], v62 src0_sel:WORD_1
	v_cvt_pk_f32_fp8_e32 v[164:165], v63
	v_cvt_pk_f32_fp8_sdwa v[62:63], v63 src0_sel:WORD_1
	s_waitcnt lgkmcnt(0)
	v_lshl_add_u32 v66, v66, 10, v204
	global_load_dwordx4 v[114:117], v66, s[98:99]
	ds_bpermute_b32 v66, v172, v185
	v_cvt_pk_f32_fp8_sdwa v[186:187], v64 src0_sel:WORD_1
	v_cvt_pk_f32_fp8_e32 v[188:189], v65
	v_pk_fma_f32 v[160:161], v[160:161], v[158:159], 0 op_sel_hi:[1,0,0]
	v_pk_fma_f32 v[162:163], v[162:163], v[158:159], 0 op_sel_hi:[1,0,0]
	s_waitcnt lgkmcnt(0)
	v_lshl_add_u32 v66, v66, 10, v204
	global_load_dwordx4 v[110:113], v66, s[98:99]
	ds_bpermute_b32 v66, v173, v185
	v_pk_fma_f32 v[164:165], v[164:165], v[158:159], 0 op_sel_hi:[1,0,0]
	v_pk_fma_f32 v[62:63], v[62:63], v[158:159], 0 op_sel_hi:[1,0,0]
	v_pk_fma_f32 v[186:187], v[186:187], v[158:159], 0 op_sel_hi:[1,0,0]
	v_pk_fma_f32 v[188:189], v[188:189], v[158:159], 0 op_sel_hi:[1,0,0]
	s_waitcnt lgkmcnt(0)
	v_lshl_add_u32 v66, v66, 10, v204
	global_load_dwordx4 v[106:109], v66, s[98:99]
	ds_bpermute_b32 v66, v175, v185
	v_cvt_pk_f32_fp8_e32 v[196:197], v60
	v_cvt_pk_f32_fp8_sdwa v[198:199], v60 src0_sel:WORD_1
	v_cvt_pk_f32_fp8_e32 v[202:203], v61
	v_cvt_pk_f32_fp8_sdwa v[60:61], v61 src0_sel:WORD_1
	s_waitcnt lgkmcnt(0)
	v_lshl_add_u32 v66, v66, 10, v204
	global_load_dwordx4 v[102:105], v66, s[98:99]
	ds_bpermute_b32 v66, v176, v185
	v_cvt_pk_f32_fp8_e32 v[190:191], v58
	v_cvt_pk_f32_fp8_sdwa v[192:193], v58 src0_sel:WORD_1
	v_cvt_pk_f32_fp8_e32 v[194:195], v59
	v_cvt_pk_f32_fp8_sdwa v[58:59], v59 src0_sel:WORD_1
	s_waitcnt lgkmcnt(0)
	v_lshl_add_u32 v66, v66, 10, v204
	global_load_dwordx4 v[98:101], v66, s[98:99]
	ds_bpermute_b32 v66, v168, v184
	s_ashr_i32 s37, s36, 31
	s_lshl_b64 s[34:35], s[36:37], 11
	s_min_i32 s0, s19, s41
	s_mul_i32 s0, s0, s39
	s_waitcnt lgkmcnt(0)
	v_lshl_add_u32 v66, v66, 10, v204
	global_load_dwordx4 v[94:97], v66, s[98:99]
	ds_bpermute_b32 v66, v169, v184
	s_add_i32 s0, s0, s33
	s_lshl_b32 s0, s0, 3
	ds_bpermute_b32 v166, v169, v183
	s_ashr_i32 s31, s30, 31
	s_waitcnt lgkmcnt(1)
	v_lshl_add_u32 v66, v66, 10, v204
	global_load_dwordx4 v[90:93], v66, s[98:99]
	ds_bpermute_b32 v66, v170, v184
	s_lshl_b64 s[30:31], s[30:31], 11
	s_add_i32 s19, s19, 2
	s_mov_b32 s36, s20
	s_waitcnt lgkmcnt(0)
	v_lshl_add_u32 v66, v66, 10, v204
	global_load_dwordx4 v[86:89], v66, s[98:99]
	ds_bpermute_b32 v66, v171, v184
	s_waitcnt lgkmcnt(0)
	v_lshl_add_u32 v66, v66, 10, v204
	global_load_dwordx4 v[82:85], v66, s[98:99]
	ds_bpermute_b32 v66, v172, v184
	s_waitcnt lgkmcnt(0)
	v_lshl_add_u32 v66, v66, 10, v204
	global_load_dwordx4 v[78:81], v66, s[98:99]
	ds_bpermute_b32 v66, v173, v184
	s_waitcnt lgkmcnt(0)
	v_lshl_add_u32 v66, v66, 10, v204
	global_load_dwordx4 v[74:77], v66, s[98:99]
	ds_bpermute_b32 v66, v175, v184
	s_waitcnt lgkmcnt(0)
	v_lshl_add_u32 v66, v66, 10, v204
	global_load_dwordx4 v[70:73], v66, s[98:99]
	ds_bpermute_b32 v66, v176, v184
	v_cvt_pk_f32_fp8_e32 v[184:185], v64
	v_cvt_pk_f32_fp8_sdwa v[64:65], v65 src0_sel:WORD_1
	v_pk_fma_f32 v[184:185], v[184:185], v[158:159], 0 op_sel_hi:[1,0,0]
	v_pk_fma_f32 v[64:65], v[64:65], v[158:159], 0 op_sel_hi:[1,0,0]
	ds_bpermute_b32 v158, v169, v155
	s_waitcnt lgkmcnt(1)
	v_lshl_add_u32 v66, v66, 10, v204
	global_load_dwordx4 v[66:69], v66, s[98:99]
	s_waitcnt lgkmcnt(0)
	v_pk_fma_f32 v[60:61], v[60:61], v[158:159], v[64:65] op_sel_hi:[1,0,1]
	ds_bpermute_b32 v64, v170, v155
	v_pk_fma_f32 v[162:163], v[192:193], v[158:159], v[162:163] op_sel_hi:[1,0,1]
	v_pk_fma_f32 v[164:165], v[194:195], v[158:159], v[164:165] op_sel_hi:[1,0,1]
	v_pk_fma_f32 v[58:59], v[58:59], v[158:159], v[62:63] op_sel_hi:[1,0,1]
	v_pk_fma_f32 v[62:63], v[196:197], v[158:159], v[184:185] op_sel_hi:[1,0,1]
	v_cvt_pk_f32_fp8_e32 v[192:193], v56
	v_cvt_pk_f32_fp8_sdwa v[194:195], v56 src0_sel:WORD_1
	v_cvt_pk_f32_fp8_e32 v[196:197], v57
	v_cvt_pk_f32_fp8_sdwa v[56:57], v57 src0_sel:WORD_1
	v_pk_fma_f32 v[160:161], v[190:191], v[158:159], v[160:161] op_sel_hi:[1,0,1]
	v_pk_fma_f32 v[184:185], v[198:199], v[158:159], v[186:187] op_sel_hi:[1,0,1]
	v_pk_fma_f32 v[186:187], v[202:203], v[158:159], v[188:189] op_sel_hi:[1,0,1]
	v_cvt_pk_f32_fp8_e32 v[158:159], v54
	v_cvt_pk_f32_fp8_sdwa v[188:189], v54 src0_sel:WORD_1
	v_cvt_pk_f32_fp8_e32 v[190:191], v55
	v_cvt_pk_f32_fp8_sdwa v[54:55], v55 src0_sel:WORD_1
	s_waitcnt lgkmcnt(0)
; DI void ev_compute(const uint4 (&v)[16], const float c0, const float c1, u16* __restrict__ yrow, const int lane) {
;   f32x2 acc[8];
; #pragma unroll
;   for (int k = 0; k < 8; ++k) acc[k] = f32x2{0.f, 0.f};
; #pragma unroll
;   for (int i = 0; i < 16; ++i) {
;     const float c = __shfl(i < 8 ? c0 : c1, (8 * i + (lane >> 3)) & 63, 64);
;     const f32x2 cc = f32x2{c, c};
;     f32x2 vf[8];
;     fp8x16_to_f32(v[i], vf);
; #pragma unroll
;     for (int k = 0; k < 8; ++k) acc[k] = __builtin_elementwise_fma(vf[k], cc, acc[k]);
;   }
	v_pk_fma_f32 v[56:57], v[56:57], v[64:65], v[60:61] op_sel_hi:[1,0,1]
	ds_bpermute_b32 v60, v171, v155
	v_pk_fma_f32 v[158:159], v[158:159], v[64:65], v[160:161] op_sel_hi:[1,0,1]
	v_pk_fma_f32 v[160:161], v[188:189], v[64:65], v[162:163] op_sel_hi:[1,0,1]
	v_pk_fma_f32 v[162:163], v[190:191], v[64:65], v[164:165] op_sel_hi:[1,0,1]
	v_pk_fma_f32 v[54:55], v[54:55], v[64:65], v[58:59] op_sel_hi:[1,0,1]
	v_pk_fma_f32 v[58:59], v[192:193], v[64:65], v[62:63] op_sel_hi:[1,0,1]
	v_cvt_pk_f32_fp8_e32 v[188:189], v52
	v_cvt_pk_f32_fp8_sdwa v[190:191], v52 src0_sel:WORD_1
	v_cvt_pk_f32_fp8_e32 v[192:193], v53
	v_cvt_pk_f32_fp8_sdwa v[52:53], v53 src0_sel:WORD_1
	v_pk_fma_f32 v[62:63], v[194:195], v[64:65], v[184:185] op_sel_hi:[1,0,1]
	v_pk_fma_f32 v[164:165], v[196:197], v[64:65], v[186:187] op_sel_hi:[1,0,1]
	v_cvt_pk_f32_fp8_e32 v[64:65], v50
	v_cvt_pk_f32_fp8_sdwa v[184:185], v50 src0_sel:WORD_1
	v_cvt_pk_f32_fp8_e32 v[186:187], v51
	v_cvt_pk_f32_fp8_sdwa v[50:51], v51 src0_sel:WORD_1
	s_waitcnt lgkmcnt(0)
	v_pk_fma_f32 v[52:53], v[52:53], v[60:61], v[56:57] op_sel_hi:[1,0,1]
	ds_bpermute_b32 v56, v172, v155
	v_pk_fma_f32 v[64:65], v[64:65], v[60:61], v[158:159] op_sel_hi:[1,0,1]
	v_pk_fma_f32 v[158:159], v[184:185], v[60:61], v[160:161] op_sel_hi:[1,0,1]
	v_pk_fma_f32 v[160:161], v[186:187], v[60:61], v[162:163] op_sel_hi:[1,0,1]
	v_pk_fma_f32 v[50:51], v[50:51], v[60:61], v[54:55] op_sel_hi:[1,0,1]
	v_pk_fma_f32 v[54:55], v[188:189], v[60:61], v[58:59] op_sel_hi:[1,0,1]
	v_cvt_pk_f32_fp8_e32 v[184:185], v48
	v_cvt_pk_f32_fp8_sdwa v[186:187], v48 src0_sel:WORD_1
	v_cvt_pk_f32_fp8_e32 v[188:189], v49
	v_cvt_pk_f32_fp8_sdwa v[48:49], v49 src0_sel:WORD_1
	v_pk_fma_f32 v[58:59], v[190:191], v[60:61], v[62:63] op_sel_hi:[1,0,1]
	v_pk_fma_f32 v[62:63], v[192:193], v[60:61], v[164:165] op_sel_hi:[1,0,1]
	v_cvt_pk_f32_fp8_e32 v[60:61], v46
	v_cvt_pk_f32_fp8_sdwa v[162:163], v46 src0_sel:WORD_1
	v_cvt_pk_f32_fp8_e32 v[164:165], v47
	v_cvt_pk_f32_fp8_sdwa v[46:47], v47 src0_sel:WORD_1
	s_waitcnt lgkmcnt(0)
	v_pk_fma_f32 v[48:49], v[48:49], v[56:57], v[52:53] op_sel_hi:[1,0,1]
	ds_bpermute_b32 v52, v173, v155
	v_pk_fma_f32 v[60:61], v[60:61], v[56:57], v[64:65] op_sel_hi:[1,0,1]
	v_pk_fma_f32 v[64:65], v[162:163], v[56:57], v[158:159] op_sel_hi:[1,0,1]
	v_pk_fma_f32 v[158:159], v[164:165], v[56:57], v[160:161] op_sel_hi:[1,0,1]
	v_pk_fma_f32 v[46:47], v[46:47], v[56:57], v[50:51] op_sel_hi:[1,0,1]
	v_pk_fma_f32 v[50:51], v[184:185], v[56:57], v[54:55] op_sel_hi:[1,0,1]
	v_cvt_pk_f32_fp8_e32 v[162:163], v44
	v_cvt_pk_f32_fp8_sdwa v[164:165], v44 src0_sel:WORD_1
	v_cvt_pk_f32_fp8_e32 v[184:185], v45
	v_cvt_pk_f32_fp8_sdwa v[44:45], v45 src0_sel:WORD_1
	v_pk_fma_f32 v[54:55], v[186:187], v[56:57], v[58:59] op_sel_hi:[1,0,1]
	v_pk_fma_f32 v[58:59], v[188:189], v[56:57], v[62:63] op_sel_hi:[1,0,1]
	v_cvt_pk_f32_fp8_e32 v[56:57], v42
	v_cvt_pk_f32_fp8_sdwa v[62:63], v42 src0_sel:WORD_1
	v_cvt_pk_f32_fp8_e32 v[160:161], v43
	v_cvt_pk_f32_fp8_sdwa v[42:43], v43 src0_sel:WORD_1
	s_waitcnt lgkmcnt(0)
	v_pk_fma_f32 v[44:45], v[44:45], v[52:53], v[48:49] op_sel_hi:[1,0,1]
	ds_bpermute_b32 v48, v175, v155
	v_pk_fma_f32 v[56:57], v[56:57], v[52:53], v[60:61] op_sel_hi:[1,0,1]
	v_pk_fma_f32 v[60:61], v[62:63], v[52:53], v[64:65] op_sel_hi:[1,0,1]
	v_pk_fma_f32 v[62:63], v[160:161], v[52:53], v[158:159] op_sel_hi:[1,0,1]
	v_pk_fma_f32 v[42:43], v[42:43], v[52:53], v[46:47] op_sel_hi:[1,0,1]
	v_pk_fma_f32 v[46:47], v[162:163], v[52:53], v[50:51] op_sel_hi:[1,0,1]
	v_cvt_pk_f32_fp8_e32 v[158:159], v40
	v_cvt_pk_f32_fp8_sdwa v[160:161], v40 src0_sel:WORD_1
	v_cvt_pk_f32_fp8_e32 v[162:163], v41
	v_cvt_pk_f32_fp8_sdwa v[40:41], v41 src0_sel:WORD_1
	v_pk_fma_f32 v[50:51], v[164:165], v[52:53], v[54:55] op_sel_hi:[1,0,1]
	v_pk_fma_f32 v[54:55], v[184:185], v[52:53], v[58:59] op_sel_hi:[1,0,1]
	v_cvt_pk_f32_fp8_e32 v[52:53], v38
	v_cvt_pk_f32_fp8_sdwa v[58:59], v38 src0_sel:WORD_1
	v_cvt_pk_f32_fp8_e32 v[64:65], v39
	v_cvt_pk_f32_fp8_sdwa v[38:39], v39 src0_sel:WORD_1
	s_waitcnt lgkmcnt(0)
	v_pk_fma_f32 v[40:41], v[40:41], v[48:49], v[44:45] op_sel_hi:[1,0,1]
	ds_bpermute_b32 v44, v176, v155
	v_pk_fma_f32 v[52:53], v[52:53], v[48:49], v[56:57] op_sel_hi:[1,0,1]
	v_pk_fma_f32 v[56:57], v[58:59], v[48:49], v[60:61] op_sel_hi:[1,0,1]
	v_pk_fma_f32 v[58:59], v[64:65], v[48:49], v[62:63] op_sel_hi:[1,0,1]
	v_pk_fma_f32 v[38:39], v[38:39], v[48:49], v[42:43] op_sel_hi:[1,0,1]
	v_pk_fma_f32 v[42:43], v[158:159], v[48:49], v[46:47] op_sel_hi:[1,0,1]
	v_cvt_pk_f32_fp8_e32 v[62:63], v36
	v_cvt_pk_f32_fp8_sdwa v[64:65], v36 src0_sel:WORD_1
	v_cvt_pk_f32_fp8_e32 v[158:159], v37
	v_cvt_pk_f32_fp8_sdwa v[36:37], v37 src0_sel:WORD_1
	v_pk_fma_f32 v[46:47], v[160:161], v[48:49], v[50:51] op_sel_hi:[1,0,1]
	v_pk_fma_f32 v[50:51], v[162:163], v[48:49], v[54:55] op_sel_hi:[1,0,1]
	v_cvt_pk_f32_fp8_e32 v[48:49], v34
	v_cvt_pk_f32_fp8_sdwa v[54:55], v34 src0_sel:WORD_1
	v_cvt_pk_f32_fp8_e32 v[60:61], v35
	v_cvt_pk_f32_fp8_sdwa v[34:35], v35 src0_sel:WORD_1
	s_waitcnt lgkmcnt(0)
	v_pk_fma_f32 v[36:37], v[36:37], v[44:45], v[40:41] op_sel_hi:[1,0,1]
	ds_bpermute_b32 v40, v168, v154
	v_pk_fma_f32 v[48:49], v[48:49], v[44:45], v[52:53] op_sel_hi:[1,0,1]
	v_pk_fma_f32 v[52:53], v[54:55], v[44:45], v[56:57] op_sel_hi:[1,0,1]
	v_pk_fma_f32 v[54:55], v[60:61], v[44:45], v[58:59] op_sel_hi:[1,0,1]
	v_pk_fma_f32 v[34:35], v[34:35], v[44:45], v[38:39] op_sel_hi:[1,0,1]
	v_pk_fma_f32 v[38:39], v[62:63], v[44:45], v[42:43] op_sel_hi:[1,0,1]
	v_cvt_pk_f32_fp8_e32 v[58:59], v32
	v_cvt_pk_f32_fp8_sdwa v[60:61], v32 src0_sel:WORD_1
	v_cvt_pk_f32_fp8_e32 v[62:63], v33
	v_cvt_pk_f32_fp8_sdwa v[32:33], v33 src0_sel:WORD_1
	v_pk_fma_f32 v[42:43], v[64:65], v[44:45], v[46:47] op_sel_hi:[1,0,1]
	v_pk_fma_f32 v[46:47], v[158:159], v[44:45], v[50:51] op_sel_hi:[1,0,1]
	v_cvt_pk_f32_fp8_e32 v[44:45], v30
	v_cvt_pk_f32_fp8_sdwa v[50:51], v30 src0_sel:WORD_1
	v_cvt_pk_f32_fp8_e32 v[56:57], v31
	v_cvt_pk_f32_fp8_sdwa v[30:31], v31 src0_sel:WORD_1
	s_waitcnt lgkmcnt(0)
; DI void ev_compute(const uint4 (&v)[16], const float c0, const float c1, u16* __restrict__ yrow, const int lane) {
;   f32x2 acc[8];
; #pragma unroll
;   for (int k = 0; k < 8; ++k) acc[k] = f32x2{0.f, 0.f};
; #pragma unroll
;   for (int i = 0; i < 16; ++i) {
;     const float c = __shfl(i < 8 ? c0 : c1, (8 * i + (lane >> 3)) & 63, 64);
;     const f32x2 cc = f32x2{c, c};
;     f32x2 vf[8];
;     fp8x16_to_f32(v[i], vf);
; #pragma unroll
;     for (int k = 0; k < 8; ++k) acc[k] = __builtin_elementwise_fma(vf[k], cc, acc[k]);
;   }
	v_pk_fma_f32 v[32:33], v[32:33], v[40:41], v[36:37] op_sel_hi:[1,0,1]
	ds_bpermute_b32 v36, v169, v154
	v_pk_fma_f32 v[44:45], v[44:45], v[40:41], v[48:49] op_sel_hi:[1,0,1]
	v_pk_fma_f32 v[48:49], v[50:51], v[40:41], v[52:53] op_sel_hi:[1,0,1]
	v_pk_fma_f32 v[50:51], v[56:57], v[40:41], v[54:55] op_sel_hi:[1,0,1]
	v_pk_fma_f32 v[30:31], v[30:31], v[40:41], v[34:35] op_sel_hi:[1,0,1]
	v_pk_fma_f32 v[34:35], v[58:59], v[40:41], v[38:39] op_sel_hi:[1,0,1]
	v_cvt_pk_f32_fp8_e32 v[54:55], v28
	v_cvt_pk_f32_fp8_sdwa v[56:57], v28 src0_sel:WORD_1
	v_cvt_pk_f32_fp8_e32 v[58:59], v29
	v_cvt_pk_f32_fp8_sdwa v[28:29], v29 src0_sel:WORD_1
	v_pk_fma_f32 v[38:39], v[60:61], v[40:41], v[42:43] op_sel_hi:[1,0,1]
	v_pk_fma_f32 v[42:43], v[62:63], v[40:41], v[46:47] op_sel_hi:[1,0,1]
	v_cvt_pk_f32_fp8_e32 v[40:41], v26
	v_cvt_pk_f32_fp8_sdwa v[46:47], v26 src0_sel:WORD_1
	v_cvt_pk_f32_fp8_e32 v[52:53], v27
	v_cvt_pk_f32_fp8_sdwa v[26:27], v27 src0_sel:WORD_1
	s_waitcnt lgkmcnt(0)
	v_pk_fma_f32 v[28:29], v[28:29], v[36:37], v[32:33] op_sel_hi:[1,0,1]
	ds_bpermute_b32 v32, v170, v154
	v_pk_fma_f32 v[40:41], v[40:41], v[36:37], v[44:45] op_sel_hi:[1,0,1]
	v_pk_fma_f32 v[44:45], v[46:47], v[36:37], v[48:49] op_sel_hi:[1,0,1]
	v_pk_fma_f32 v[46:47], v[52:53], v[36:37], v[50:51] op_sel_hi:[1,0,1]
	v_pk_fma_f32 v[26:27], v[26:27], v[36:37], v[30:31] op_sel_hi:[1,0,1]
	v_pk_fma_f32 v[30:31], v[54:55], v[36:37], v[34:35] op_sel_hi:[1,0,1]
	v_cvt_pk_f32_fp8_e32 v[50:51], v24
	v_cvt_pk_f32_fp8_sdwa v[52:53], v24 src0_sel:WORD_1
	v_cvt_pk_f32_fp8_e32 v[54:55], v25
	v_cvt_pk_f32_fp8_sdwa v[24:25], v25 src0_sel:WORD_1
	v_pk_fma_f32 v[34:35], v[56:57], v[36:37], v[38:39] op_sel_hi:[1,0,1]
	v_pk_fma_f32 v[38:39], v[58:59], v[36:37], v[42:43] op_sel_hi:[1,0,1]
	v_cvt_pk_f32_fp8_e32 v[36:37], v22
	v_cvt_pk_f32_fp8_sdwa v[42:43], v22 src0_sel:WORD_1
	v_cvt_pk_f32_fp8_e32 v[48:49], v23
	v_cvt_pk_f32_fp8_sdwa v[22:23], v23 src0_sel:WORD_1
	s_waitcnt lgkmcnt(0)
	v_pk_fma_f32 v[24:25], v[24:25], v[32:33], v[28:29] op_sel_hi:[1,0,1]
	ds_bpermute_b32 v28, v171, v154
	v_pk_fma_f32 v[36:37], v[36:37], v[32:33], v[40:41] op_sel_hi:[1,0,1]
	v_pk_fma_f32 v[40:41], v[42:43], v[32:33], v[44:45] op_sel_hi:[1,0,1]
	v_pk_fma_f32 v[42:43], v[48:49], v[32:33], v[46:47] op_sel_hi:[1,0,1]
	v_pk_fma_f32 v[22:23], v[22:23], v[32:33], v[26:27] op_sel_hi:[1,0,1]
	v_pk_fma_f32 v[26:27], v[50:51], v[32:33], v[30:31] op_sel_hi:[1,0,1]
	v_cvt_pk_f32_fp8_e32 v[46:47], v20
	v_cvt_pk_f32_fp8_sdwa v[48:49], v20 src0_sel:WORD_1
	v_cvt_pk_f32_fp8_e32 v[50:51], v21
	v_cvt_pk_f32_fp8_sdwa v[20:21], v21 src0_sel:WORD_1
	v_pk_fma_f32 v[30:31], v[52:53], v[32:33], v[34:35] op_sel_hi:[1,0,1]
	v_pk_fma_f32 v[34:35], v[54:55], v[32:33], v[38:39] op_sel_hi:[1,0,1]
	v_cvt_pk_f32_fp8_e32 v[32:33], v18
	v_cvt_pk_f32_fp8_sdwa v[38:39], v18 src0_sel:WORD_1
	v_cvt_pk_f32_fp8_e32 v[44:45], v19
	v_cvt_pk_f32_fp8_sdwa v[18:19], v19 src0_sel:WORD_1
	s_waitcnt lgkmcnt(0)
	v_pk_fma_f32 v[20:21], v[20:21], v[28:29], v[24:25] op_sel_hi:[1,0,1]
	ds_bpermute_b32 v24, v172, v154
	v_pk_fma_f32 v[32:33], v[32:33], v[28:29], v[36:37] op_sel_hi:[1,0,1]
	v_pk_fma_f32 v[36:37], v[38:39], v[28:29], v[40:41] op_sel_hi:[1,0,1]
	v_pk_fma_f32 v[38:39], v[44:45], v[28:29], v[42:43] op_sel_hi:[1,0,1]
	v_pk_fma_f32 v[18:19], v[18:19], v[28:29], v[22:23] op_sel_hi:[1,0,1]
	v_pk_fma_f32 v[22:23], v[46:47], v[28:29], v[26:27] op_sel_hi:[1,0,1]
	v_cvt_pk_f32_fp8_e32 v[42:43], v16
	v_cvt_pk_f32_fp8_sdwa v[44:45], v16 src0_sel:WORD_1
	v_cvt_pk_f32_fp8_e32 v[46:47], v17
	v_cvt_pk_f32_fp8_sdwa v[16:17], v17 src0_sel:WORD_1
	v_pk_fma_f32 v[26:27], v[48:49], v[28:29], v[30:31] op_sel_hi:[1,0,1]
	v_pk_fma_f32 v[30:31], v[50:51], v[28:29], v[34:35] op_sel_hi:[1,0,1]
	v_cvt_pk_f32_fp8_e32 v[28:29], v14
	v_cvt_pk_f32_fp8_sdwa v[34:35], v14 src0_sel:WORD_1
	v_cvt_pk_f32_fp8_e32 v[40:41], v15
	v_cvt_pk_f32_fp8_sdwa v[14:15], v15 src0_sel:WORD_1
	s_waitcnt lgkmcnt(0)
	v_pk_fma_f32 v[16:17], v[16:17], v[24:25], v[20:21] op_sel_hi:[1,0,1]
	ds_bpermute_b32 v20, v173, v154
	v_pk_fma_f32 v[28:29], v[28:29], v[24:25], v[32:33] op_sel_hi:[1,0,1]
	v_pk_fma_f32 v[32:33], v[34:35], v[24:25], v[36:37] op_sel_hi:[1,0,1]
	v_pk_fma_f32 v[34:35], v[40:41], v[24:25], v[38:39] op_sel_hi:[1,0,1]
	v_pk_fma_f32 v[14:15], v[14:15], v[24:25], v[18:19] op_sel_hi:[1,0,1]
	v_pk_fma_f32 v[18:19], v[42:43], v[24:25], v[22:23] op_sel_hi:[1,0,1]
	v_cvt_pk_f32_fp8_e32 v[38:39], v12
	v_cvt_pk_f32_fp8_sdwa v[40:41], v12 src0_sel:WORD_1
	v_cvt_pk_f32_fp8_e32 v[42:43], v13
	v_cvt_pk_f32_fp8_sdwa v[12:13], v13 src0_sel:WORD_1
	v_pk_fma_f32 v[22:23], v[44:45], v[24:25], v[26:27] op_sel_hi:[1,0,1]
	v_pk_fma_f32 v[26:27], v[46:47], v[24:25], v[30:31] op_sel_hi:[1,0,1]
	v_cvt_pk_f32_fp8_e32 v[24:25], v10
	v_cvt_pk_f32_fp8_sdwa v[30:31], v10 src0_sel:WORD_1
	v_cvt_pk_f32_fp8_e32 v[36:37], v11
	v_cvt_pk_f32_fp8_sdwa v[10:11], v11 src0_sel:WORD_1
	s_waitcnt lgkmcnt(0)
	v_pk_fma_f32 v[12:13], v[12:13], v[20:21], v[16:17] op_sel_hi:[1,0,1]
	ds_bpermute_b32 v16, v175, v154
	v_pk_fma_f32 v[24:25], v[24:25], v[20:21], v[28:29] op_sel_hi:[1,0,1]
	v_pk_fma_f32 v[28:29], v[30:31], v[20:21], v[32:33] op_sel_hi:[1,0,1]
	v_pk_fma_f32 v[30:31], v[36:37], v[20:21], v[34:35] op_sel_hi:[1,0,1]
	v_pk_fma_f32 v[10:11], v[10:11], v[20:21], v[14:15] op_sel_hi:[1,0,1]
	v_pk_fma_f32 v[14:15], v[38:39], v[20:21], v[18:19] op_sel_hi:[1,0,1]
	v_cvt_pk_f32_fp8_e32 v[34:35], v8
	v_cvt_pk_f32_fp8_sdwa v[36:37], v8 src0_sel:WORD_1
	v_cvt_pk_f32_fp8_e32 v[38:39], v9
	v_cvt_pk_f32_fp8_sdwa v[8:9], v9 src0_sel:WORD_1
	v_pk_fma_f32 v[18:19], v[40:41], v[20:21], v[22:23] op_sel_hi:[1,0,1]
	v_pk_fma_f32 v[22:23], v[42:43], v[20:21], v[26:27] op_sel_hi:[1,0,1]
	v_cvt_pk_f32_fp8_e32 v[20:21], v6
	v_cvt_pk_f32_fp8_sdwa v[26:27], v6 src0_sel:WORD_1
	v_cvt_pk_f32_fp8_e32 v[32:33], v7
	v_cvt_pk_f32_fp8_sdwa v[6:7], v7 src0_sel:WORD_1
	s_waitcnt lgkmcnt(0)
; DI unsigned pack2(float a, float b) { const f32x2 v = {a, b}; const bf16x2_t r = __builtin_convertvector(v, bf16x2_t); return __builtin_bit_cast(unsigned, r); }
; DI void ev_load(const unsigned char* __restrict__ vb8, const int id0, const int id1, const int cs, const int lane, uint4 (&v)[16]) {
; #pragma unroll
;   for (int i = 0; i < 16; ++i) {
;     const int id = __shfl(i < 8 ? id0 : id1, (8 * i + (lane >> 3)) & 63, 64);
;     v[i] = *(const uint4*)(vb8 + (size_t)id * 1024 + 128 * cs + 16 * (lane & 7));
;   }
; }
; DI void ev_compute(const uint4 (&v)[16], const float c0, const float c1, u16* __restrict__ yrow, const int lane) {
;     ...
;   float a[16];
; #pragma unroll
;   for (int k = 0; k < 8; ++k) { a[2 * k] = acc[k][0]; a[2 * k + 1] = acc[k][1]; }
;   float q8[8], q4[4], q2[2];
;   const bool b5 = lane & 32, b4 = lane & 16, b3 = lane & 8;
; #pragma unroll
;   for (int j = 0; j < 8; ++j) { const float keep = b5 ? a[8 + j] : a[j], send = b5 ? a[j] : a[8 + j]; q8[j] = keep + __shfl_xor(send, 32, 64); }
; #pragma unroll
;   for (int j = 0; j < 4; ++j) { const float keep = b4 ? q8[4 + j] : q8[j], send = b4 ? q8[j] : q8[4 + j]; q4[j] = keep + __shfl_xor(send, 16, 64); }
; #pragma unroll
;   for (int j = 0; j < 2; ++j) { const float keep = b3 ? q4[2 + j] : q4[j], send = b3 ? q4[j] : q4[2 + j]; q2[j] = keep + __shfl_xor(send, 8, 64); }
;   *(unsigned*)(yrow + 16 * (lane & 7) + 2 * (lane >> 3)) = pack2(q2[0], q2[1]);
	v_pk_fma_f32 v[8:9], v[8:9], v[16:17], v[12:13] op_sel_hi:[1,0,1]
	ds_bpermute_b32 v12, v176, v154
	v_pk_fma_f32 v[20:21], v[20:21], v[16:17], v[24:25] op_sel_hi:[1,0,1]
	v_pk_fma_f32 v[24:25], v[26:27], v[16:17], v[28:29] op_sel_hi:[1,0,1]
	v_pk_fma_f32 v[26:27], v[32:33], v[16:17], v[30:31] op_sel_hi:[1,0,1]
	v_pk_fma_f32 v[6:7], v[6:7], v[16:17], v[10:11] op_sel_hi:[1,0,1]
	v_pk_fma_f32 v[10:11], v[34:35], v[16:17], v[14:15] op_sel_hi:[1,0,1]
	v_pk_fma_f32 v[14:15], v[36:37], v[16:17], v[18:19] op_sel_hi:[1,0,1]
	v_pk_fma_f32 v[18:19], v[38:39], v[16:17], v[22:23] op_sel_hi:[1,0,1]
	v_cvt_pk_f32_fp8_e32 v[16:17], v2
	v_cvt_pk_f32_fp8_sdwa v[22:23], v2 src0_sel:WORD_1
	v_cvt_pk_f32_fp8_e32 v[28:29], v3
	v_cvt_pk_f32_fp8_sdwa v[2:3], v3 src0_sel:WORD_1
	v_cvt_pk_f32_fp8_e32 v[30:31], v4
	v_cvt_pk_f32_fp8_sdwa v[32:33], v4 src0_sel:WORD_1
	v_cvt_pk_f32_fp8_e32 v[34:35], v5
	v_cvt_pk_f32_fp8_sdwa v[4:5], v5 src0_sel:WORD_1
	s_waitcnt lgkmcnt(0)
	v_pk_fma_f32 v[16:17], v[16:17], v[12:13], v[20:21] op_sel_hi:[1,0,1]
	v_pk_fma_f32 v[2:3], v[2:3], v[12:13], v[6:7] op_sel_hi:[1,0,1]
	v_pk_fma_f32 v[6:7], v[30:31], v[12:13], v[10:11] op_sel_hi:[1,0,1]
	v_pk_fma_f32 v[20:21], v[22:23], v[12:13], v[24:25] op_sel_hi:[1,0,1]
	v_pk_fma_f32 v[22:23], v[28:29], v[12:13], v[26:27] op_sel_hi:[1,0,1]
	v_pk_fma_f32 v[10:11], v[32:33], v[12:13], v[14:15] op_sel_hi:[1,0,1]
	v_pk_fma_f32 v[14:15], v[34:35], v[12:13], v[18:19] op_sel_hi:[1,0,1]
	v_pk_fma_f32 v[4:5], v[4:5], v[12:13], v[8:9] op_sel_hi:[1,0,1]
	s_nop 1
	v_permlane32_swap_b32_e32 v16, v6
	v_permlane32_swap_b32_e32 v17, v7
	v_permlane32_swap_b32_e32 v20, v10
	v_permlane32_swap_b32_e32 v21, v11
	v_permlane32_swap_b32_e32 v22, v14
	v_permlane32_swap_b32_e32 v23, v15
	v_permlane32_swap_b32_e32 v2, v4
	v_permlane32_swap_b32_e32 v3, v5
	v_pk_add_f32 v[6:7], v[16:17], v[6:7]
	v_pk_add_f32 v[8:9], v[20:21], v[10:11]
	v_pk_add_f32 v[10:11], v[22:23], v[14:15]
	v_pk_add_f32 v[2:3], v[2:3], v[4:5]
	v_cndmask_b32_e64 v4, v6, v10, s[8:9]
	v_cndmask_b32_e64 v12, v10, v6, s[8:9]
	v_cndmask_b32_e64 v5, v7, v11, s[8:9]
	v_cndmask_b32_e64 v6, v8, v2, s[8:9]
	v_cndmask_b32_e64 v10, v2, v8, s[8:9]
	v_cndmask_b32_e64 v2, v9, v3, s[8:9]
	ds_bpermute_b32 v4, v178, v4
	v_cndmask_b32_e64 v13, v11, v7, s[8:9]
	ds_bpermute_b32 v5, v178, v5
	ds_bpermute_b32 v6, v178, v6
	ds_bpermute_b32 v7, v178, v2
	v_cndmask_b32_e64 v11, v3, v9, s[8:9]
	ds_bpermute_b32 v164, v168, v183
	s_waitcnt lgkmcnt(3)
	v_pk_add_f32 v[4:5], v[12:13], v[4:5]
	s_waitcnt vmcnt(19)
	v_cvt_pk_f32_fp8_sdwa v[160:161], v127 src0_sel:WORD_1
	s_waitcnt lgkmcnt(1)
	v_pk_add_f32 v[2:3], v[10:11], v[6:7]
	v_cvt_pk_f32_fp8_e32 v[162:163], v128
	v_cndmask_b32_e64 v6, v4, v2, s[10:11]
	v_cndmask_b32_e64 v8, v2, v4, s[10:11]
	v_cndmask_b32_e64 v2, v5, v3, s[10:11]
	ds_bpermute_b32 v6, v179, v6
	ds_bpermute_b32 v7, v179, v2
	v_cndmask_b32_e64 v9, v3, v5, s[10:11]
	v_cvt_pk_f32_fp8_sdwa v[188:189], v128 src0_sel:WORD_1
	v_cvt_pk_f32_fp8_e32 v[190:191], v129
	v_cvt_pk_f32_fp8_sdwa v[192:193], v129 src0_sel:WORD_1
	s_waitcnt lgkmcnt(0)
	v_pk_add_f32 v[2:3], v[8:9], v[6:7]
	s_waitcnt vmcnt(16)
	v_cvt_pk_f32_fp8_e32 v[194:195], v124
	v_cvt_pk_bf16_f32 v4, v2, v3
	v_lshl_add_u64 v[2:3], v[152:153], 0, s[34:35]
	global_store_dword v[2:3], v4, off
	ds_bpermute_b32 v2, v168, v157
	s_add_i32 s34, s0, s38
	s_ashr_i32 s35, s34, 31
	s_lshl_b64 s[0:1], s[34:35], 9
	v_or_b32_e32 v154, s0, v174
	s_waitcnt lgkmcnt(0)
	v_lshl_add_u32 v2, v2, 10, v204
	global_load_dwordx4 v[62:65], v2, s[98:99]
	ds_bpermute_b32 v2, v169, v157
	v_mov_b32_e32 v155, s1
	v_cvt_pk_f32_fp8_sdwa v[196:197], v124 src0_sel:WORD_1
	v_cvt_pk_f32_fp8_e32 v[198:199], v125
	v_cvt_pk_f32_fp8_sdwa v[124:125], v125 src0_sel:WORD_1
	s_waitcnt lgkmcnt(0)
	v_lshl_add_u32 v2, v2, 10, v204
	global_load_dwordx4 v[58:61], v2, s[98:99]
	ds_bpermute_b32 v2, v170, v157
	s_cmp_lt_i32 s24, s40
	s_waitcnt lgkmcnt(0)
	v_lshl_add_u32 v2, v2, 10, v204
	global_load_dwordx4 v[54:57], v2, s[98:99]
	ds_bpermute_b32 v2, v171, v157
	s_waitcnt lgkmcnt(0)
	v_lshl_add_u32 v2, v2, 10, v204
	global_load_dwordx4 v[50:53], v2, s[98:99]
	ds_bpermute_b32 v2, v172, v157
	s_waitcnt lgkmcnt(0)
	v_lshl_add_u32 v2, v2, 10, v204
	global_load_dwordx4 v[46:49], v2, s[98:99]
	ds_bpermute_b32 v2, v173, v157
	s_waitcnt lgkmcnt(0)
	v_lshl_add_u32 v2, v2, 10, v204
	global_load_dwordx4 v[42:45], v2, s[98:99]
	ds_bpermute_b32 v2, v175, v157
	s_waitcnt lgkmcnt(0)
	v_lshl_add_u32 v2, v2, 10, v204
	global_load_dwordx4 v[38:41], v2, s[98:99]
	ds_bpermute_b32 v2, v176, v157
	s_waitcnt lgkmcnt(0)
	v_lshl_add_u32 v2, v2, 10, v204
	global_load_dwordx4 v[34:37], v2, s[98:99]
	s_waitcnt vmcnt(22)
	ds_bpermute_b32 v2, v168, v156
	s_waitcnt lgkmcnt(0)
	v_lshl_add_u32 v2, v2, 10, v204
	global_load_dwordx4 v[30:33], v2, s[98:99]
	ds_bpermute_b32 v2, v169, v156
	s_waitcnt lgkmcnt(0)
	v_lshl_add_u32 v2, v2, 10, v204
	global_load_dwordx4 v[26:29], v2, s[98:99]
	ds_bpermute_b32 v2, v170, v156
	s_waitcnt lgkmcnt(0)
	v_lshl_add_u32 v2, v2, 10, v204
	global_load_dwordx4 v[22:25], v2, s[98:99]
	ds_bpermute_b32 v2, v171, v156
	s_waitcnt lgkmcnt(0)
	v_lshl_add_u32 v2, v2, 10, v204
	global_load_dwordx4 v[18:21], v2, s[98:99]
	ds_bpermute_b32 v2, v172, v156
	s_waitcnt lgkmcnt(0)
	v_lshl_add_u32 v2, v2, 10, v204
	global_load_dwordx4 v[14:17], v2, s[98:99]
	ds_bpermute_b32 v2, v173, v156
	s_waitcnt lgkmcnt(0)
	v_lshl_add_u32 v2, v2, 10, v204
	global_load_dwordx4 v[10:13], v2, s[98:99]
	ds_bpermute_b32 v2, v175, v156
	s_waitcnt lgkmcnt(0)
	v_lshl_add_u32 v2, v2, 10, v204
	global_load_dwordx4 v[6:9], v2, s[98:99]
	ds_bpermute_b32 v2, v176, v156
	v_lshl_add_u64 v[156:157], s[26:27], 0, v[154:155]
	global_load_dword v185, v[156:157], off
	v_or_b32_e32 v156, 0x100, v154
	v_mov_b32_e32 v157, s1
	s_waitcnt lgkmcnt(0)
; DI void ev_compute(const uint4 (&v)[16], const float c0, const float c1, u16* __restrict__ yrow, const int lane) {
;   f32x2 acc[8];
; #pragma unroll
;   for (int k = 0; k < 8; ++k) acc[k] = f32x2{0.f, 0.f};
; #pragma unroll
;   for (int i = 0; i < 16; ++i) {
;     const float c = __shfl(i < 8 ? c0 : c1, (8 * i + (lane >> 3)) & 63, 64);
;     const f32x2 cc = f32x2{c, c};
;     f32x2 vf[8];
;     fp8x16_to_f32(v[i], vf);
; #pragma unroll
;     for (int k = 0; k < 8; ++k) acc[k] = __builtin_elementwise_fma(vf[k], cc, acc[k]);
;   }
	v_lshl_add_u32 v2, v2, 10, v204
	v_lshl_add_u64 v[158:159], s[26:27], 0, v[156:157]
	v_lshl_add_u64 v[154:155], s[28:29], 0, v[154:155]
	global_load_dwordx4 v[2:5], v2, s[98:99]
	s_nop 0
	global_load_dword v184, v[158:159], off
	global_load_dword v186, v[154:155], off
	v_lshl_add_u64 v[154:155], s[28:29], 0, v[156:157]
	global_load_dword v187, v[154:155], off
	v_cvt_pk_f32_fp8_e32 v[154:155], v126
	v_cvt_pk_f32_fp8_sdwa v[156:157], v126 src0_sel:WORD_1
	v_cvt_pk_f32_fp8_e32 v[158:159], v127
	v_pk_fma_f32 v[126:127], v[154:155], v[164:165], 0 op_sel_hi:[1,0,0]
	v_pk_fma_f32 v[128:129], v[156:157], v[164:165], 0 op_sel_hi:[1,0,0]
	v_pk_fma_f32 v[154:155], v[158:159], v[164:165], 0 op_sel_hi:[1,0,0]
	v_pk_fma_f32 v[156:157], v[160:161], v[164:165], 0 op_sel_hi:[1,0,0]
	v_pk_fma_f32 v[158:159], v[162:163], v[164:165], 0 op_sel_hi:[1,0,0]
	v_pk_fma_f32 v[160:161], v[188:189], v[164:165], 0 op_sel_hi:[1,0,0]
	v_pk_fma_f32 v[162:163], v[190:191], v[164:165], 0 op_sel_hi:[1,0,0]
	v_pk_fma_f32 v[164:165], v[192:193], v[164:165], 0 op_sel_hi:[1,0,0]
	v_cvt_pk_f32_fp8_e32 v[188:189], v122
	v_cvt_pk_f32_fp8_sdwa v[190:191], v122 src0_sel:WORD_1
	v_cvt_pk_f32_fp8_e32 v[192:193], v123
	v_cvt_pk_f32_fp8_sdwa v[122:123], v123 src0_sel:WORD_1
	v_pk_fma_f32 v[126:127], v[188:189], v[166:167], v[126:127] op_sel_hi:[1,0,1]
	v_pk_fma_f32 v[128:129], v[190:191], v[166:167], v[128:129] op_sel_hi:[1,0,1]
	v_pk_fma_f32 v[154:155], v[192:193], v[166:167], v[154:155] op_sel_hi:[1,0,1]
	v_pk_fma_f32 v[122:123], v[122:123], v[166:167], v[156:157] op_sel_hi:[1,0,1]
	v_pk_fma_f32 v[156:157], v[194:195], v[166:167], v[158:159] op_sel_hi:[1,0,1]
	v_pk_fma_f32 v[158:159], v[196:197], v[166:167], v[160:161] op_sel_hi:[1,0,1]
	v_pk_fma_f32 v[160:161], v[198:199], v[166:167], v[162:163] op_sel_hi:[1,0,1]
	ds_bpermute_b32 v162, v170, v183
	v_cvt_pk_f32_fp8_e32 v[192:193], v120
	v_cvt_pk_f32_fp8_sdwa v[194:195], v120 src0_sel:WORD_1
	v_cvt_pk_f32_fp8_e32 v[196:197], v121
	v_cvt_pk_f32_fp8_sdwa v[120:121], v121 src0_sel:WORD_1
	v_pk_fma_f32 v[124:125], v[124:125], v[166:167], v[164:165] op_sel_hi:[1,0,1]
	v_cvt_pk_f32_fp8_e32 v[164:165], v118
	v_cvt_pk_f32_fp8_sdwa v[188:189], v118 src0_sel:WORD_1
	v_cvt_pk_f32_fp8_e32 v[190:191], v119
	v_cvt_pk_f32_fp8_sdwa v[118:119], v119 src0_sel:WORD_1
	s_waitcnt lgkmcnt(0)
	v_pk_fma_f32 v[120:121], v[120:121], v[162:163], v[124:125] op_sel_hi:[1,0,1]
	ds_bpermute_b32 v124, v171, v183
	v_pk_fma_f32 v[128:129], v[188:189], v[162:163], v[128:129] op_sel_hi:[1,0,1]
	v_pk_fma_f32 v[154:155], v[190:191], v[162:163], v[154:155] op_sel_hi:[1,0,1]
	v_pk_fma_f32 v[118:119], v[118:119], v[162:163], v[122:123] op_sel_hi:[1,0,1]
	v_pk_fma_f32 v[122:123], v[192:193], v[162:163], v[156:157] op_sel_hi:[1,0,1]
	s_waitcnt vmcnt(33)
	v_cvt_pk_f32_fp8_e32 v[188:189], v116
	v_cvt_pk_f32_fp8_sdwa v[190:191], v116 src0_sel:WORD_1
	v_cvt_pk_f32_fp8_e32 v[192:193], v117
	v_cvt_pk_f32_fp8_sdwa v[116:117], v117 src0_sel:WORD_1
	v_pk_fma_f32 v[126:127], v[164:165], v[162:163], v[126:127] op_sel_hi:[1,0,1]
	v_pk_fma_f32 v[156:157], v[194:195], v[162:163], v[158:159] op_sel_hi:[1,0,1]
	v_pk_fma_f32 v[158:159], v[196:197], v[162:163], v[160:161] op_sel_hi:[1,0,1]
	v_cvt_pk_f32_fp8_e32 v[160:161], v114
	v_cvt_pk_f32_fp8_sdwa v[162:163], v114 src0_sel:WORD_1
	v_cvt_pk_f32_fp8_e32 v[164:165], v115
	v_cvt_pk_f32_fp8_sdwa v[114:115], v115 src0_sel:WORD_1
	s_waitcnt lgkmcnt(0)
	v_pk_fma_f32 v[116:117], v[116:117], v[124:125], v[120:121] op_sel_hi:[1,0,1]
	ds_bpermute_b32 v120, v172, v183
	v_pk_fma_f32 v[128:129], v[162:163], v[124:125], v[128:129] op_sel_hi:[1,0,1]
	v_pk_fma_f32 v[154:155], v[164:165], v[124:125], v[154:155] op_sel_hi:[1,0,1]
	v_pk_fma_f32 v[114:115], v[114:115], v[124:125], v[118:119] op_sel_hi:[1,0,1]
	v_pk_fma_f32 v[118:119], v[188:189], v[124:125], v[122:123] op_sel_hi:[1,0,1]
	s_waitcnt vmcnt(32)
	v_cvt_pk_f32_fp8_e32 v[162:163], v112
	v_cvt_pk_f32_fp8_sdwa v[164:165], v112 src0_sel:WORD_1
	v_cvt_pk_f32_fp8_e32 v[188:189], v113
	v_cvt_pk_f32_fp8_sdwa v[112:113], v113 src0_sel:WORD_1
	v_pk_fma_f32 v[126:127], v[160:161], v[124:125], v[126:127] op_sel_hi:[1,0,1]
	v_pk_fma_f32 v[122:123], v[190:191], v[124:125], v[156:157] op_sel_hi:[1,0,1]
	v_pk_fma_f32 v[156:157], v[192:193], v[124:125], v[158:159] op_sel_hi:[1,0,1]
	v_cvt_pk_f32_fp8_e32 v[124:125], v110
	v_cvt_pk_f32_fp8_sdwa v[158:159], v110 src0_sel:WORD_1
	v_cvt_pk_f32_fp8_e32 v[160:161], v111
	v_cvt_pk_f32_fp8_sdwa v[110:111], v111 src0_sel:WORD_1
	s_waitcnt lgkmcnt(0)
	v_pk_fma_f32 v[112:113], v[112:113], v[120:121], v[116:117] op_sel_hi:[1,0,1]
	ds_bpermute_b32 v116, v173, v183
	v_pk_fma_f32 v[124:125], v[124:125], v[120:121], v[126:127] op_sel_hi:[1,0,1]
	v_pk_fma_f32 v[126:127], v[158:159], v[120:121], v[128:129] op_sel_hi:[1,0,1]
	v_pk_fma_f32 v[128:129], v[160:161], v[120:121], v[154:155] op_sel_hi:[1,0,1]
	v_pk_fma_f32 v[110:111], v[110:111], v[120:121], v[114:115] op_sel_hi:[1,0,1]
	v_pk_fma_f32 v[114:115], v[162:163], v[120:121], v[118:119] op_sel_hi:[1,0,1]
	s_waitcnt vmcnt(31)
	v_cvt_pk_f32_fp8_e32 v[158:159], v108
	v_cvt_pk_f32_fp8_sdwa v[160:161], v108 src0_sel:WORD_1
	v_cvt_pk_f32_fp8_e32 v[162:163], v109
	v_cvt_pk_f32_fp8_sdwa v[108:109], v109 src0_sel:WORD_1
	v_pk_fma_f32 v[118:119], v[164:165], v[120:121], v[122:123] op_sel_hi:[1,0,1]
	v_pk_fma_f32 v[122:123], v[188:189], v[120:121], v[156:157] op_sel_hi:[1,0,1]
	v_cvt_pk_f32_fp8_e32 v[120:121], v106
	v_cvt_pk_f32_fp8_sdwa v[154:155], v106 src0_sel:WORD_1
	v_cvt_pk_f32_fp8_e32 v[156:157], v107
	v_cvt_pk_f32_fp8_sdwa v[106:107], v107 src0_sel:WORD_1
	s_waitcnt lgkmcnt(0)
; DI void ev_compute(const uint4 (&v)[16], const float c0, const float c1, u16* __restrict__ yrow, const int lane) {
;   f32x2 acc[8];
; #pragma unroll
;   for (int k = 0; k < 8; ++k) acc[k] = f32x2{0.f, 0.f};
; #pragma unroll
;   for (int i = 0; i < 16; ++i) {
;     const float c = __shfl(i < 8 ? c0 : c1, (8 * i + (lane >> 3)) & 63, 64);
;     const f32x2 cc = f32x2{c, c};
;     f32x2 vf[8];
;     fp8x16_to_f32(v[i], vf);
; #pragma unroll
;     for (int k = 0; k < 8; ++k) acc[k] = __builtin_elementwise_fma(vf[k], cc, acc[k]);
;   }
	v_pk_fma_f32 v[108:109], v[108:109], v[116:117], v[112:113] op_sel_hi:[1,0,1]
	ds_bpermute_b32 v112, v175, v183
	v_pk_fma_f32 v[120:121], v[120:121], v[116:117], v[124:125] op_sel_hi:[1,0,1]
	v_pk_fma_f32 v[124:125], v[154:155], v[116:117], v[126:127] op_sel_hi:[1,0,1]
	v_pk_fma_f32 v[126:127], v[156:157], v[116:117], v[128:129] op_sel_hi:[1,0,1]
	v_pk_fma_f32 v[106:107], v[106:107], v[116:117], v[110:111] op_sel_hi:[1,0,1]
	v_pk_fma_f32 v[110:111], v[158:159], v[116:117], v[114:115] op_sel_hi:[1,0,1]
	s_waitcnt vmcnt(30)
	v_cvt_pk_f32_fp8_e32 v[154:155], v104
	v_cvt_pk_f32_fp8_sdwa v[156:157], v104 src0_sel:WORD_1
	v_cvt_pk_f32_fp8_e32 v[158:159], v105
	v_cvt_pk_f32_fp8_sdwa v[104:105], v105 src0_sel:WORD_1
	v_pk_fma_f32 v[114:115], v[160:161], v[116:117], v[118:119] op_sel_hi:[1,0,1]
	v_pk_fma_f32 v[118:119], v[162:163], v[116:117], v[122:123] op_sel_hi:[1,0,1]
	v_cvt_pk_f32_fp8_e32 v[116:117], v102
	v_cvt_pk_f32_fp8_sdwa v[122:123], v102 src0_sel:WORD_1
	v_cvt_pk_f32_fp8_e32 v[128:129], v103
	v_cvt_pk_f32_fp8_sdwa v[102:103], v103 src0_sel:WORD_1
	s_waitcnt lgkmcnt(0)
	v_pk_fma_f32 v[104:105], v[104:105], v[112:113], v[108:109] op_sel_hi:[1,0,1]
	ds_bpermute_b32 v108, v176, v183
	v_pk_fma_f32 v[116:117], v[116:117], v[112:113], v[120:121] op_sel_hi:[1,0,1]
	v_pk_fma_f32 v[120:121], v[122:123], v[112:113], v[124:125] op_sel_hi:[1,0,1]
	v_pk_fma_f32 v[122:123], v[128:129], v[112:113], v[126:127] op_sel_hi:[1,0,1]
	v_pk_fma_f32 v[102:103], v[102:103], v[112:113], v[106:107] op_sel_hi:[1,0,1]
	v_pk_fma_f32 v[106:107], v[154:155], v[112:113], v[110:111] op_sel_hi:[1,0,1]
	s_waitcnt vmcnt(29)
	v_cvt_pk_f32_fp8_e32 v[126:127], v100
	v_cvt_pk_f32_fp8_sdwa v[128:129], v100 src0_sel:WORD_1
	v_cvt_pk_f32_fp8_e32 v[154:155], v101
	v_cvt_pk_f32_fp8_sdwa v[100:101], v101 src0_sel:WORD_1
	v_pk_fma_f32 v[110:111], v[156:157], v[112:113], v[114:115] op_sel_hi:[1,0,1]
	v_pk_fma_f32 v[114:115], v[158:159], v[112:113], v[118:119] op_sel_hi:[1,0,1]
	v_cvt_pk_f32_fp8_e32 v[112:113], v98
	v_cvt_pk_f32_fp8_sdwa v[118:119], v98 src0_sel:WORD_1
	v_cvt_pk_f32_fp8_e32 v[124:125], v99
	v_cvt_pk_f32_fp8_sdwa v[98:99], v99 src0_sel:WORD_1
	s_waitcnt lgkmcnt(0)
	v_pk_fma_f32 v[100:101], v[100:101], v[108:109], v[104:105] op_sel_hi:[1,0,1]
	ds_bpermute_b32 v104, v168, v180
	v_pk_fma_f32 v[112:113], v[112:113], v[108:109], v[116:117] op_sel_hi:[1,0,1]
	v_pk_fma_f32 v[116:117], v[118:119], v[108:109], v[120:121] op_sel_hi:[1,0,1]
	v_pk_fma_f32 v[118:119], v[124:125], v[108:109], v[122:123] op_sel_hi:[1,0,1]
	v_pk_fma_f32 v[98:99], v[98:99], v[108:109], v[102:103] op_sel_hi:[1,0,1]
	v_pk_fma_f32 v[102:103], v[126:127], v[108:109], v[106:107] op_sel_hi:[1,0,1]
	s_waitcnt vmcnt(28)
	v_cvt_pk_f32_fp8_e32 v[122:123], v96
	v_cvt_pk_f32_fp8_sdwa v[124:125], v96 src0_sel:WORD_1
	v_cvt_pk_f32_fp8_e32 v[126:127], v97
	v_cvt_pk_f32_fp8_sdwa v[96:97], v97 src0_sel:WORD_1
	v_pk_fma_f32 v[106:107], v[128:129], v[108:109], v[110:111] op_sel_hi:[1,0,1]
	v_pk_fma_f32 v[110:111], v[154:155], v[108:109], v[114:115] op_sel_hi:[1,0,1]
	v_cvt_pk_f32_fp8_e32 v[108:109], v94
	v_cvt_pk_f32_fp8_sdwa v[114:115], v94 src0_sel:WORD_1
	v_cvt_pk_f32_fp8_e32 v[120:121], v95
	v_cvt_pk_f32_fp8_sdwa v[94:95], v95 src0_sel:WORD_1
	s_waitcnt lgkmcnt(0)
	v_pk_fma_f32 v[96:97], v[96:97], v[104:105], v[100:101] op_sel_hi:[1,0,1]
	ds_bpermute_b32 v100, v169, v180
	v_pk_fma_f32 v[108:109], v[108:109], v[104:105], v[112:113] op_sel_hi:[1,0,1]
	v_pk_fma_f32 v[112:113], v[114:115], v[104:105], v[116:117] op_sel_hi:[1,0,1]
	v_pk_fma_f32 v[114:115], v[120:121], v[104:105], v[118:119] op_sel_hi:[1,0,1]
	v_pk_fma_f32 v[94:95], v[94:95], v[104:105], v[98:99] op_sel_hi:[1,0,1]
	v_pk_fma_f32 v[98:99], v[122:123], v[104:105], v[102:103] op_sel_hi:[1,0,1]
	s_waitcnt vmcnt(27)
	v_cvt_pk_f32_fp8_e32 v[118:119], v92
	v_cvt_pk_f32_fp8_sdwa v[120:121], v92 src0_sel:WORD_1
	v_cvt_pk_f32_fp8_e32 v[122:123], v93
	v_cvt_pk_f32_fp8_sdwa v[92:93], v93 src0_sel:WORD_1
	v_pk_fma_f32 v[102:103], v[124:125], v[104:105], v[106:107] op_sel_hi:[1,0,1]
	v_pk_fma_f32 v[106:107], v[126:127], v[104:105], v[110:111] op_sel_hi:[1,0,1]
	v_cvt_pk_f32_fp8_e32 v[104:105], v90
	v_cvt_pk_f32_fp8_sdwa v[110:111], v90 src0_sel:WORD_1
	v_cvt_pk_f32_fp8_e32 v[116:117], v91
	v_cvt_pk_f32_fp8_sdwa v[90:91], v91 src0_sel:WORD_1
	s_waitcnt lgkmcnt(0)
	v_pk_fma_f32 v[92:93], v[92:93], v[100:101], v[96:97] op_sel_hi:[1,0,1]
	ds_bpermute_b32 v96, v170, v180
	v_pk_fma_f32 v[104:105], v[104:105], v[100:101], v[108:109] op_sel_hi:[1,0,1]
	v_pk_fma_f32 v[108:109], v[110:111], v[100:101], v[112:113] op_sel_hi:[1,0,1]
	v_pk_fma_f32 v[110:111], v[116:117], v[100:101], v[114:115] op_sel_hi:[1,0,1]
	v_pk_fma_f32 v[90:91], v[90:91], v[100:101], v[94:95] op_sel_hi:[1,0,1]
	v_pk_fma_f32 v[94:95], v[118:119], v[100:101], v[98:99] op_sel_hi:[1,0,1]
	s_waitcnt vmcnt(26)
	v_cvt_pk_f32_fp8_e32 v[114:115], v88
	v_cvt_pk_f32_fp8_sdwa v[116:117], v88 src0_sel:WORD_1
	v_cvt_pk_f32_fp8_e32 v[118:119], v89
	v_cvt_pk_f32_fp8_sdwa v[88:89], v89 src0_sel:WORD_1
	v_pk_fma_f32 v[98:99], v[120:121], v[100:101], v[102:103] op_sel_hi:[1,0,1]
	v_pk_fma_f32 v[102:103], v[122:123], v[100:101], v[106:107] op_sel_hi:[1,0,1]
	v_cvt_pk_f32_fp8_e32 v[100:101], v86
	v_cvt_pk_f32_fp8_sdwa v[106:107], v86 src0_sel:WORD_1
	v_cvt_pk_f32_fp8_e32 v[112:113], v87
	v_cvt_pk_f32_fp8_sdwa v[86:87], v87 src0_sel:WORD_1
	s_waitcnt lgkmcnt(0)
	v_pk_fma_f32 v[88:89], v[88:89], v[96:97], v[92:93] op_sel_hi:[1,0,1]
	ds_bpermute_b32 v92, v171, v180
	v_pk_fma_f32 v[100:101], v[100:101], v[96:97], v[104:105] op_sel_hi:[1,0,1]
	v_pk_fma_f32 v[104:105], v[106:107], v[96:97], v[108:109] op_sel_hi:[1,0,1]
	v_pk_fma_f32 v[106:107], v[112:113], v[96:97], v[110:111] op_sel_hi:[1,0,1]
	v_pk_fma_f32 v[86:87], v[86:87], v[96:97], v[90:91] op_sel_hi:[1,0,1]
	v_pk_fma_f32 v[90:91], v[114:115], v[96:97], v[94:95] op_sel_hi:[1,0,1]
	s_waitcnt vmcnt(25)
; DI unsigned pack2(float a, float b) { const f32x2 v = {a, b}; const bf16x2_t r = __builtin_convertvector(v, bf16x2_t); return __builtin_bit_cast(unsigned, r); }
; DI void ev_compute(const uint4 (&v)[16], const float c0, const float c1, u16* __restrict__ yrow, const int lane) {
;   f32x2 acc[8];
; #pragma unroll
;   for (int k = 0; k < 8; ++k) acc[k] = f32x2{0.f, 0.f};
; #pragma unroll
;   for (int i = 0; i < 16; ++i) {
;     const float c = __shfl(i < 8 ? c0 : c1, (8 * i + (lane >> 3)) & 63, 64);
;     const f32x2 cc = f32x2{c, c};
;     f32x2 vf[8];
;     fp8x16_to_f32(v[i], vf);
; #pragma unroll
;     for (int k = 0; k < 8; ++k) acc[k] = __builtin_elementwise_fma(vf[k], cc, acc[k]);
;   }
;   float a[16];
; #pragma unroll
;   for (int k = 0; k < 8; ++k) { a[2 * k] = acc[k][0]; a[2 * k + 1] = acc[k][1]; }
;   float q8[8], q4[4], q2[2];
;   const bool b5 = lane & 32, b4 = lane & 16, b3 = lane & 8;
; #pragma unroll
;   for (int j = 0; j < 8; ++j) { const float keep = b5 ? a[8 + j] : a[j], send = b5 ? a[j] : a[8 + j]; q8[j] = keep + __shfl_xor(send, 32, 64); }
; #pragma unroll
;   for (int j = 0; j < 4; ++j) { const float keep = b4 ? q8[4 + j] : q8[j], send = b4 ? q8[j] : q8[4 + j]; q4[j] = keep + __shfl_xor(send, 16, 64); }
; #pragma unroll
;   for (int j = 0; j < 2; ++j) { const float keep = b3 ? q4[2 + j] : q4[j], send = b3 ? q4[j] : q4[2 + j]; q2[j] = keep + __shfl_xor(send, 8, 64); }
;   *(unsigned*)(yrow + 16 * (lane & 7) + 2 * (lane >> 3)) = pack2(q2[0], q2[1]);
; DI void phase_ev(const Params& p, const unsigned my_xcc, const unsigned my_rank) {
;     ...
;       ev_compute(vB, cb0, cb1, ybuf + (size_t)tB * 1024 + 128 * cs, lane);
;       tA = tA2; a0 = na0; a1 = na1; ca0 = nca0; ca1 = nca1; tB = tB2; b0 = nb0; b1 = nb1; cb0 = ncb0; cb1 = ncb1;
	v_cvt_pk_f32_fp8_e32 v[110:111], v84
	v_cvt_pk_f32_fp8_sdwa v[112:113], v84 src0_sel:WORD_1
	v_cvt_pk_f32_fp8_e32 v[114:115], v85
	v_cvt_pk_f32_fp8_sdwa v[84:85], v85 src0_sel:WORD_1
	v_pk_fma_f32 v[94:95], v[116:117], v[96:97], v[98:99] op_sel_hi:[1,0,1]
	v_pk_fma_f32 v[98:99], v[118:119], v[96:97], v[102:103] op_sel_hi:[1,0,1]
	v_cvt_pk_f32_fp8_e32 v[96:97], v82
	v_cvt_pk_f32_fp8_sdwa v[102:103], v82 src0_sel:WORD_1
	v_cvt_pk_f32_fp8_e32 v[108:109], v83
	v_cvt_pk_f32_fp8_sdwa v[82:83], v83 src0_sel:WORD_1
	s_waitcnt lgkmcnt(0)
	v_pk_fma_f32 v[84:85], v[84:85], v[92:93], v[88:89] op_sel_hi:[1,0,1]
	ds_bpermute_b32 v88, v172, v180
	v_pk_fma_f32 v[96:97], v[96:97], v[92:93], v[100:101] op_sel_hi:[1,0,1]
	v_pk_fma_f32 v[100:101], v[102:103], v[92:93], v[104:105] op_sel_hi:[1,0,1]
	v_pk_fma_f32 v[102:103], v[108:109], v[92:93], v[106:107] op_sel_hi:[1,0,1]
	v_pk_fma_f32 v[82:83], v[82:83], v[92:93], v[86:87] op_sel_hi:[1,0,1]
	v_pk_fma_f32 v[86:87], v[110:111], v[92:93], v[90:91] op_sel_hi:[1,0,1]
	s_waitcnt vmcnt(24)
	v_cvt_pk_f32_fp8_e32 v[106:107], v80
	v_cvt_pk_f32_fp8_sdwa v[108:109], v80 src0_sel:WORD_1
	v_cvt_pk_f32_fp8_e32 v[110:111], v81
	v_cvt_pk_f32_fp8_sdwa v[80:81], v81 src0_sel:WORD_1
	v_pk_fma_f32 v[90:91], v[112:113], v[92:93], v[94:95] op_sel_hi:[1,0,1]
	v_pk_fma_f32 v[94:95], v[114:115], v[92:93], v[98:99] op_sel_hi:[1,0,1]
	v_cvt_pk_f32_fp8_e32 v[92:93], v78
	v_cvt_pk_f32_fp8_sdwa v[98:99], v78 src0_sel:WORD_1
	v_cvt_pk_f32_fp8_e32 v[104:105], v79
	v_cvt_pk_f32_fp8_sdwa v[78:79], v79 src0_sel:WORD_1
	s_waitcnt lgkmcnt(0)
	v_pk_fma_f32 v[80:81], v[80:81], v[88:89], v[84:85] op_sel_hi:[1,0,1]
	ds_bpermute_b32 v84, v173, v180
	v_pk_fma_f32 v[92:93], v[92:93], v[88:89], v[96:97] op_sel_hi:[1,0,1]
	v_pk_fma_f32 v[96:97], v[98:99], v[88:89], v[100:101] op_sel_hi:[1,0,1]
	v_pk_fma_f32 v[98:99], v[104:105], v[88:89], v[102:103] op_sel_hi:[1,0,1]
	v_pk_fma_f32 v[78:79], v[78:79], v[88:89], v[82:83] op_sel_hi:[1,0,1]
	v_pk_fma_f32 v[82:83], v[106:107], v[88:89], v[86:87] op_sel_hi:[1,0,1]
	s_waitcnt vmcnt(23)
	v_cvt_pk_f32_fp8_e32 v[102:103], v76
	v_cvt_pk_f32_fp8_sdwa v[104:105], v76 src0_sel:WORD_1
	v_cvt_pk_f32_fp8_e32 v[106:107], v77
	v_cvt_pk_f32_fp8_sdwa v[76:77], v77 src0_sel:WORD_1
	v_pk_fma_f32 v[86:87], v[108:109], v[88:89], v[90:91] op_sel_hi:[1,0,1]
	v_pk_fma_f32 v[90:91], v[110:111], v[88:89], v[94:95] op_sel_hi:[1,0,1]
	v_cvt_pk_f32_fp8_e32 v[88:89], v74
	v_cvt_pk_f32_fp8_sdwa v[94:95], v74 src0_sel:WORD_1
	v_cvt_pk_f32_fp8_e32 v[100:101], v75
	v_cvt_pk_f32_fp8_sdwa v[74:75], v75 src0_sel:WORD_1
	s_waitcnt lgkmcnt(0)
	v_pk_fma_f32 v[76:77], v[76:77], v[84:85], v[80:81] op_sel_hi:[1,0,1]
	ds_bpermute_b32 v80, v175, v180
	v_pk_fma_f32 v[88:89], v[88:89], v[84:85], v[92:93] op_sel_hi:[1,0,1]
	v_pk_fma_f32 v[92:93], v[94:95], v[84:85], v[96:97] op_sel_hi:[1,0,1]
	v_pk_fma_f32 v[94:95], v[100:101], v[84:85], v[98:99] op_sel_hi:[1,0,1]
	v_pk_fma_f32 v[74:75], v[74:75], v[84:85], v[78:79] op_sel_hi:[1,0,1]
	v_pk_fma_f32 v[78:79], v[102:103], v[84:85], v[82:83] op_sel_hi:[1,0,1]
	s_waitcnt vmcnt(22)
	v_cvt_pk_f32_fp8_e32 v[98:99], v72
	v_cvt_pk_f32_fp8_sdwa v[100:101], v72 src0_sel:WORD_1
	v_cvt_pk_f32_fp8_e32 v[102:103], v73
	v_cvt_pk_f32_fp8_sdwa v[72:73], v73 src0_sel:WORD_1
	v_pk_fma_f32 v[82:83], v[104:105], v[84:85], v[86:87] op_sel_hi:[1,0,1]
	v_pk_fma_f32 v[86:87], v[106:107], v[84:85], v[90:91] op_sel_hi:[1,0,1]
	v_cvt_pk_f32_fp8_e32 v[84:85], v70
	v_cvt_pk_f32_fp8_sdwa v[90:91], v70 src0_sel:WORD_1
	v_cvt_pk_f32_fp8_e32 v[96:97], v71
	v_cvt_pk_f32_fp8_sdwa v[70:71], v71 src0_sel:WORD_1
	s_waitcnt lgkmcnt(0)
	v_pk_fma_f32 v[72:73], v[72:73], v[80:81], v[76:77] op_sel_hi:[1,0,1]
	ds_bpermute_b32 v76, v176, v180
	v_pk_fma_f32 v[84:85], v[84:85], v[80:81], v[88:89] op_sel_hi:[1,0,1]
	v_pk_fma_f32 v[88:89], v[90:91], v[80:81], v[92:93] op_sel_hi:[1,0,1]
	v_pk_fma_f32 v[90:91], v[96:97], v[80:81], v[94:95] op_sel_hi:[1,0,1]
	v_pk_fma_f32 v[70:71], v[70:71], v[80:81], v[74:75] op_sel_hi:[1,0,1]
	v_pk_fma_f32 v[74:75], v[98:99], v[80:81], v[78:79] op_sel_hi:[1,0,1]
	v_pk_fma_f32 v[78:79], v[100:101], v[80:81], v[82:83] op_sel_hi:[1,0,1]
	v_pk_fma_f32 v[82:83], v[102:103], v[80:81], v[86:87] op_sel_hi:[1,0,1]
	s_waitcnt vmcnt(21)
	v_cvt_pk_f32_fp8_e32 v[80:81], v66
	v_cvt_pk_f32_fp8_sdwa v[86:87], v66 src0_sel:WORD_1
	v_cvt_pk_f32_fp8_e32 v[92:93], v67
	v_cvt_pk_f32_fp8_sdwa v[66:67], v67 src0_sel:WORD_1
	v_cvt_pk_f32_fp8_e32 v[94:95], v68
	v_cvt_pk_f32_fp8_sdwa v[96:97], v68 src0_sel:WORD_1
	v_cvt_pk_f32_fp8_e32 v[98:99], v69
	v_cvt_pk_f32_fp8_sdwa v[68:69], v69 src0_sel:WORD_1
	s_waitcnt lgkmcnt(0)
	v_pk_fma_f32 v[80:81], v[80:81], v[76:77], v[84:85] op_sel_hi:[1,0,1]
	v_pk_fma_f32 v[66:67], v[66:67], v[76:77], v[70:71] op_sel_hi:[1,0,1]
	v_pk_fma_f32 v[70:71], v[94:95], v[76:77], v[74:75] op_sel_hi:[1,0,1]
	v_pk_fma_f32 v[84:85], v[86:87], v[76:77], v[88:89] op_sel_hi:[1,0,1]
	v_pk_fma_f32 v[86:87], v[92:93], v[76:77], v[90:91] op_sel_hi:[1,0,1]
	v_pk_fma_f32 v[74:75], v[96:97], v[76:77], v[78:79] op_sel_hi:[1,0,1]
	v_pk_fma_f32 v[78:79], v[98:99], v[76:77], v[82:83] op_sel_hi:[1,0,1]
	v_pk_fma_f32 v[68:69], v[68:69], v[76:77], v[72:73] op_sel_hi:[1,0,1]
	s_nop 1
	v_permlane32_swap_b32_e32 v80, v70
	v_permlane32_swap_b32_e32 v81, v71
	v_permlane32_swap_b32_e32 v84, v74
	v_permlane32_swap_b32_e32 v85, v75
	v_permlane32_swap_b32_e32 v86, v78
	v_permlane32_swap_b32_e32 v87, v79
	v_permlane32_swap_b32_e32 v66, v68
	v_permlane32_swap_b32_e32 v67, v69
	v_pk_add_f32 v[70:71], v[80:81], v[70:71]
	v_pk_add_f32 v[72:73], v[84:85], v[74:75]
	v_pk_add_f32 v[74:75], v[86:87], v[78:79]
	v_pk_add_f32 v[66:67], v[66:67], v[68:69]
	v_cndmask_b32_e64 v68, v70, v74, s[8:9]
	v_cndmask_b32_e64 v76, v74, v70, s[8:9]
	v_cndmask_b32_e64 v69, v71, v75, s[8:9]
	v_cndmask_b32_e64 v70, v72, v66, s[8:9]
	v_cndmask_b32_e64 v74, v66, v72, s[8:9]
	v_cndmask_b32_e64 v66, v73, v67, s[8:9]
	ds_bpermute_b32 v68, v178, v68
	v_cndmask_b32_e64 v77, v75, v71, s[8:9]
	ds_bpermute_b32 v69, v178, v69
	ds_bpermute_b32 v70, v178, v70
	ds_bpermute_b32 v71, v178, v66
	v_cndmask_b32_e64 v75, v67, v73, s[8:9]
	v_mov_b32_e32 v155, v181
	s_waitcnt lgkmcnt(2)
	v_pk_add_f32 v[68:69], v[76:77], v[68:69]
	v_mov_b32_e32 v154, v182
	s_waitcnt lgkmcnt(0)
	v_pk_add_f32 v[66:67], v[74:75], v[70:71]
	s_waitcnt vmcnt(0)
	v_mov_b32_e32 v180, v187
	v_cndmask_b32_e64 v70, v68, v66, s[10:11]
	v_cndmask_b32_e64 v72, v66, v68, s[10:11]
	v_cndmask_b32_e64 v66, v69, v67, s[10:11]
	ds_bpermute_b32 v70, v179, v70
	ds_bpermute_b32 v71, v179, v66
	v_cndmask_b32_e64 v73, v67, v69, s[10:11]
	v_mov_b32_e32 v183, v186
	s_waitcnt lgkmcnt(0)
	v_pk_add_f32 v[66:67], v[72:73], v[70:71]
	s_nop 0
	v_cvt_pk_bf16_f32 v68, v66, v67
	v_lshl_add_u64 v[66:67], v[152:153], 0, s[30:31]
	s_mov_b32 s30, s34
	global_store_dword v[66:67], v68, off
	s_cbranch_scc1 .LBB0_570
	s_branch .LBB0_566
